# K loop: leading register set-up of each load segment (LDS/DMA addresses, m0) moved before the barrier into free gaps of the preceding MFMA block
# speedup vs baseline: 1.0104x; 1.0036x over previous
.LBB0_522:
	s_add_i32 vcc_lo, s74, 2
	s_add_u32 s76, s72, 0x80
	s_addc_u32 s75, s73, 0
	s_add_i32 vcc_hi, 0, 0x10000
	v_add_u32_e32 v140, vcc_hi, v237
	s_waitcnt lgkmcnt(0)
	ds_read_b128 v[128:131], v140
	ds_read_b128 v[132:135], v140 offset:1024
	ds_read_b128 v[136:139], v140 offset:2048
	ds_read_b128 v[140:143], v140 offset:3072
	s_cmp_eq_u32 s50, s74
	s_cselect_b32 s74, s68, s76
	s_cselect_b32 s75, s69, s75
	s_cselect_b32 s77, s71, s79
	s_cselect_b32 s76, s70, s78
	v_lshl_add_u64 v[176:177], s[72:73], 0, v[206:207]
	s_add_i32 m0, s93, 0xc000
	ds_read_b128 v[144:147], v240
	ds_read_b128 v[148:151], v240 offset:1024
	ds_read_b128 v[152:155], v240 offset:2048
	ds_read_b128 v[156:159], v240 offset:3072
	ds_read_b128 v[160:163], v240 offset:4096
	ds_read_b128 v[164:167], v240 offset:5120
	ds_read_b128 v[168:171], v240 offset:6144
	ds_read_b128 v[172:175], v240 offset:7168
	global_load_lds_dwordx4 v[176:177], off
	v_lshl_add_u64 v[176:177], s[72:73], 0, v[208:209]
	s_add_i32 m0, s93, 0xe000
	s_nop 0
	global_load_lds_dwordx4 v[176:177], off
	s_waitcnt lgkmcnt(8)
	s_barrier
	s_waitcnt lgkmcnt(0)
	v_mfma_f32_16x16x32_bf16 v[124:127], v[128:131], v[144:147], v[124:127]
	v_mfma_f32_16x16x32_bf16 v[120:123], v[136:139], v[144:147], v[120:123]
	v_mfma_f32_16x16x32_bf16 v[116:119], v[128:131], v[152:155], v[116:119]
	v_mfma_f32_16x16x32_bf16 v[112:115], v[136:139], v[152:155], v[112:115]
	v_mfma_f32_16x16x32_bf16 v[100:103], v[128:131], v[160:163], v[100:103]
	v_mfma_f32_16x16x32_bf16 v[96:99], v[136:139], v[160:163], v[96:99]
	v_mfma_f32_16x16x32_bf16 v[84:87], v[128:131], v[168:171], v[84:87]
	v_mfma_f32_16x16x32_bf16 v[80:83], v[136:139], v[168:171], v[80:83]
	v_mfma_f32_16x16x32_bf16 v[124:127], v[132:135], v[148:151], v[124:127]
	s_add_i32 s31, 0, 0x14000
	v_mfma_f32_16x16x32_bf16 v[120:123], v[140:143], v[148:151], v[120:123]
	s_add_i32 vcc_hi, vcc_hi, s87
	v_mfma_f32_16x16x32_bf16 v[116:119], v[132:135], v[156:159], v[116:119]
	v_add_u32_e32 v188, s31, v237
	v_mfma_f32_16x16x32_bf16 v[112:115], v[140:143], v[156:159], v[112:115]
	v_lshl_add_u64 v[210:211], s[76:77], 0, v[196:197]
	v_mfma_f32_16x16x32_bf16 v[100:103], v[132:135], v[164:167], v[100:103]
	s_mov_b32 m0, vcc_hi
	v_mfma_f32_16x16x32_bf16 v[96:99], v[140:143], v[164:167], v[96:99]
	v_mfma_f32_16x16x32_bf16 v[84:87], v[132:135], v[172:175], v[84:87]
	v_mfma_f32_16x16x32_bf16 v[80:83], v[140:143], v[172:175], v[80:83]
	s_barrier
	ds_read_b128 v[176:179], v188
	ds_read_b128 v[180:183], v188 offset:1024
	ds_read_b128 v[184:187], v188 offset:2048
	ds_read_b128 v[188:191], v188 offset:3072
	global_load_lds_dwordx4 v[210:211], off
	v_lshl_add_u64 v[212:213], s[76:77], 0, v[200:201]
	s_add_i32 m0, vcc_hi, 0x2000
	s_nop 0
	global_load_lds_dwordx4 v[212:213], off
	s_barrier
	s_waitcnt lgkmcnt(0)
	v_mfma_f32_16x16x32_bf16 v[108:111], v[176:179], v[144:147], v[108:111]
	v_mfma_f32_16x16x32_bf16 v[104:107], v[184:187], v[144:147], v[104:107]
	v_mfma_f32_16x16x32_bf16 v[92:95], v[176:179], v[152:155], v[92:95]
	v_mfma_f32_16x16x32_bf16 v[88:91], v[184:187], v[152:155], v[88:91]
	v_mfma_f32_16x16x32_bf16 v[76:79], v[176:179], v[160:163], v[76:79]
	v_mfma_f32_16x16x32_bf16 v[72:75], v[184:187], v[160:163], v[72:75]
	v_mfma_f32_16x16x32_bf16 v[68:71], v[176:179], v[168:171], v[68:71]
	v_mfma_f32_16x16x32_bf16 v[64:67], v[184:187], v[168:171], v[64:67]
	v_mfma_f32_16x16x32_bf16 v[108:111], v[180:183], v[148:151], v[108:111]
	s_mov_b32 m0, s93
	v_mfma_f32_16x16x32_bf16 v[104:107], v[188:191], v[148:151], v[104:107]
	v_lshl_add_u64 v[214:215], s[74:75], 0, v[194:195]
	v_mfma_f32_16x16x32_bf16 v[92:95], v[180:183], v[156:159], v[92:95]
	v_mfma_f32_16x16x32_bf16 v[88:91], v[188:191], v[156:159], v[88:91]
	v_mfma_f32_16x16x32_bf16 v[76:79], v[180:183], v[164:167], v[76:79]
	v_mfma_f32_16x16x32_bf16 v[72:75], v[188:191], v[164:167], v[72:75]
	v_mfma_f32_16x16x32_bf16 v[68:71], v[180:183], v[172:175], v[68:71]
	v_mfma_f32_16x16x32_bf16 v[64:67], v[188:191], v[172:175], v[64:67]
	s_barrier
	ds_read_b128 v[144:147], v240 offset:16384
	ds_read_b128 v[148:151], v240 offset:17408
	ds_read_b128 v[152:155], v240 offset:18432
	ds_read_b128 v[156:159], v240 offset:19456
	ds_read_b128 v[160:163], v240 offset:20480
	ds_read_b128 v[164:167], v240 offset:21504
	ds_read_b128 v[168:171], v240 offset:22528
	ds_read_b128 v[172:175], v240 offset:23552
	global_load_lds_dwordx4 v[214:215], off
	v_lshl_add_u64 v[216:217], s[74:75], 0, v[198:199]
	s_mov_b32 m0, s54
	s_nop 0
	global_load_lds_dwordx4 v[216:217], off
	s_barrier
	s_waitcnt lgkmcnt(0)
	v_mfma_f32_16x16x32_bf16 v[60:63], v[128:131], v[144:147], v[60:63]
	v_mfma_f32_16x16x32_bf16 v[56:59], v[136:139], v[144:147], v[56:59]
	v_mfma_f32_16x16x32_bf16 v[52:55], v[128:131], v[152:155], v[52:55]
	v_mfma_f32_16x16x32_bf16 v[48:51], v[136:139], v[152:155], v[48:51]
	v_mfma_f32_16x16x32_bf16 v[36:39], v[128:131], v[160:163], v[36:39]
	v_mfma_f32_16x16x32_bf16 v[32:35], v[136:139], v[160:163], v[32:35]
	v_mfma_f32_16x16x32_bf16 v[20:23], v[128:131], v[168:171], v[20:23]
	v_mfma_f32_16x16x32_bf16 v[16:19], v[136:139], v[168:171], v[16:19]
	v_mfma_f32_16x16x32_bf16 v[60:63], v[132:135], v[148:151], v[60:63]
	s_add_u32 s76, s76, s20
	v_mfma_f32_16x16x32_bf16 v[56:59], v[140:143], v[148:151], v[56:59]
	s_addc_u32 s77, s77, 0
	v_mfma_f32_16x16x32_bf16 v[52:55], v[132:135], v[156:159], v[52:55]
	s_add_i32 s31, s31, s87
	v_mfma_f32_16x16x32_bf16 v[48:51], v[140:143], v[156:159], v[48:51]
	v_lshl_add_u64 v[218:219], s[76:77], 0, v[196:197]
	v_mfma_f32_16x16x32_bf16 v[36:39], v[132:135], v[164:167], v[36:39]
	s_mov_b32 m0, s31
	v_mfma_f32_16x16x32_bf16 v[32:35], v[140:143], v[164:167], v[32:35]
	v_lshl_add_u64 v[220:221], s[76:77], 0, v[200:201]
	v_mfma_f32_16x16x32_bf16 v[20:23], v[132:135], v[172:175], v[20:23]
	v_mfma_f32_16x16x32_bf16 v[16:19], v[140:143], v[172:175], v[16:19]
	s_barrier
	global_load_lds_dwordx4 v[218:219], off
	s_add_i32 m0, s31, 0x2000
	s_nop 0
	global_load_lds_dwordx4 v[220:221], off
	s_waitcnt vmcnt(6)
	s_barrier
	v_mfma_f32_16x16x32_bf16 v[44:47], v[176:179], v[144:147], v[44:47]
	v_mfma_f32_16x16x32_bf16 v[40:43], v[184:187], v[144:147], v[40:43]
	v_mfma_f32_16x16x32_bf16 v[28:31], v[176:179], v[152:155], v[28:31]
	v_mfma_f32_16x16x32_bf16 v[24:27], v[184:187], v[152:155], v[24:27]
	v_mfma_f32_16x16x32_bf16 v[12:15], v[176:179], v[160:163], v[12:15]
	v_mfma_f32_16x16x32_bf16 v[8:11], v[184:187], v[160:163], v[8:11]
	v_mfma_f32_16x16x32_bf16 v[4:7], v[176:179], v[168:171], v[4:7]
	v_mfma_f32_16x16x32_bf16 v[0:3], v[184:187], v[168:171], v[0:3]
	v_mfma_f32_16x16x32_bf16 v[44:47], v[180:183], v[148:151], v[44:47]
	s_add_i32 s31, 0, 0x18000
	v_mfma_f32_16x16x32_bf16 v[40:43], v[188:191], v[148:151], v[40:43]
	v_add_u32_e32 v140, s31, v237
	v_mfma_f32_16x16x32_bf16 v[28:31], v[180:183], v[156:159], v[28:31]
	v_mfma_f32_16x16x32_bf16 v[24:27], v[188:191], v[156:159], v[24:27]
	v_mfma_f32_16x16x32_bf16 v[12:15], v[180:183], v[164:167], v[12:15]
	v_mfma_f32_16x16x32_bf16 v[8:11], v[188:191], v[164:167], v[8:11]
	v_mfma_f32_16x16x32_bf16 v[4:7], v[180:183], v[172:175], v[4:7]
	v_mfma_f32_16x16x32_bf16 v[0:3], v[188:191], v[172:175], v[0:3]
	s_barrier
	ds_read_b128 v[128:131], v140
	ds_read_b128 v[132:135], v140 offset:1024
	ds_read_b128 v[136:139], v140 offset:2048
	ds_read_b128 v[140:143], v140 offset:3072
	s_add_u32 s74, s74, s20
	s_addc_u32 s75, s75, 0
	s_mov_b32 m0, s34
	v_lshl_add_u64 v[176:177], s[74:75], 0, v[194:195]
	ds_read_b128 v[144:147], v240 offset:32768
	ds_read_b128 v[148:151], v240 offset:33792
	ds_read_b128 v[152:155], v240 offset:34816
	ds_read_b128 v[156:159], v240 offset:35840
	ds_read_b128 v[160:163], v240 offset:36864
	ds_read_b128 v[164:167], v240 offset:37888
	ds_read_b128 v[168:171], v240 offset:38912
	ds_read_b128 v[172:175], v240 offset:39936
	global_load_lds_dwordx4 v[176:177], off
	v_lshl_add_u64 v[176:177], s[74:75], 0, v[198:199]
	s_mov_b32 m0, s35
	s_nop 0
	global_load_lds_dwordx4 v[176:177], off
	s_waitcnt lgkmcnt(8)
	s_barrier
	s_waitcnt lgkmcnt(0)
	v_mfma_f32_16x16x32_bf16 v[124:127], v[128:131], v[144:147], v[124:127]
	v_mfma_f32_16x16x32_bf16 v[120:123], v[136:139], v[144:147], v[120:123]
	v_mfma_f32_16x16x32_bf16 v[116:119], v[128:131], v[152:155], v[116:119]
	v_mfma_f32_16x16x32_bf16 v[112:115], v[136:139], v[152:155], v[112:115]
	v_mfma_f32_16x16x32_bf16 v[100:103], v[128:131], v[160:163], v[100:103]
	v_mfma_f32_16x16x32_bf16 v[96:99], v[136:139], v[160:163], v[96:99]
	v_mfma_f32_16x16x32_bf16 v[84:87], v[128:131], v[168:171], v[84:87]
	v_mfma_f32_16x16x32_bf16 v[80:83], v[136:139], v[168:171], v[80:83]
	v_mfma_f32_16x16x32_bf16 v[124:127], v[132:135], v[148:151], v[124:127]
	s_add_i32 s74, 0, 0x1c000
	v_mfma_f32_16x16x32_bf16 v[120:123], v[140:143], v[148:151], v[120:123]
	s_add_i32 s31, s31, s87
	v_mfma_f32_16x16x32_bf16 v[116:119], v[132:135], v[156:159], v[116:119]
	v_add_u32_e32 v188, s74, v237
	v_mfma_f32_16x16x32_bf16 v[112:115], v[140:143], v[156:159], v[112:115]
	v_lshl_add_u64 v[210:211], v[210:211], 0, s[60:61]
	v_mfma_f32_16x16x32_bf16 v[100:103], v[132:135], v[164:167], v[100:103]
	s_mov_b32 m0, s31
	v_mfma_f32_16x16x32_bf16 v[96:99], v[140:143], v[164:167], v[96:99]
	v_mfma_f32_16x16x32_bf16 v[84:87], v[132:135], v[172:175], v[84:87]
	v_mfma_f32_16x16x32_bf16 v[80:83], v[140:143], v[172:175], v[80:83]
	s_barrier
	ds_read_b128 v[176:179], v188
	ds_read_b128 v[180:183], v188 offset:1024
	ds_read_b128 v[184:187], v188 offset:2048
	ds_read_b128 v[188:191], v188 offset:3072
	global_load_lds_dwordx4 v[210:211], off
	v_lshl_add_u64 v[210:211], v[212:213], 0, s[60:61]
	s_add_i32 m0, s31, 0x2000
	s_nop 0
	global_load_lds_dwordx4 v[210:211], off
	s_barrier
	s_waitcnt lgkmcnt(0)
	v_mfma_f32_16x16x32_bf16 v[108:111], v[176:179], v[144:147], v[108:111]
	v_mfma_f32_16x16x32_bf16 v[104:107], v[184:187], v[144:147], v[104:107]
	v_mfma_f32_16x16x32_bf16 v[92:95], v[176:179], v[152:155], v[92:95]
	v_mfma_f32_16x16x32_bf16 v[88:91], v[184:187], v[152:155], v[88:91]
	v_mfma_f32_16x16x32_bf16 v[76:79], v[176:179], v[160:163], v[76:79]
	v_mfma_f32_16x16x32_bf16 v[72:75], v[184:187], v[160:163], v[72:75]
	v_mfma_f32_16x16x32_bf16 v[68:71], v[176:179], v[168:171], v[68:71]
	v_mfma_f32_16x16x32_bf16 v[64:67], v[184:187], v[168:171], v[64:67]
	v_mfma_f32_16x16x32_bf16 v[108:111], v[180:183], v[148:151], v[108:111]
	s_mov_b32 m0, s97
	v_mfma_f32_16x16x32_bf16 v[104:107], v[188:191], v[148:151], v[104:107]
	v_lshl_add_u64 v[210:211], v[214:215], 0, s[60:61]
	v_mfma_f32_16x16x32_bf16 v[92:95], v[180:183], v[156:159], v[92:95]
	v_mfma_f32_16x16x32_bf16 v[88:91], v[188:191], v[156:159], v[88:91]
	v_mfma_f32_16x16x32_bf16 v[76:79], v[180:183], v[164:167], v[76:79]
	v_mfma_f32_16x16x32_bf16 v[72:75], v[188:191], v[164:167], v[72:75]
	v_mfma_f32_16x16x32_bf16 v[68:71], v[180:183], v[172:175], v[68:71]
	v_mfma_f32_16x16x32_bf16 v[64:67], v[188:191], v[172:175], v[64:67]
	s_barrier
	ds_read_b128 v[144:147], v240 offset:49152
	ds_read_b128 v[148:151], v240 offset:50176
	ds_read_b128 v[152:155], v240 offset:51200
	ds_read_b128 v[156:159], v240 offset:52224
	ds_read_b128 v[160:163], v240 offset:53248
	ds_read_b128 v[164:167], v240 offset:54272
	ds_read_b128 v[168:171], v240 offset:55296
	ds_read_b128 v[172:175], v240 offset:56320
	global_load_lds_dwordx4 v[210:211], off
	v_lshl_add_u64 v[210:211], v[216:217], 0, s[60:61]
	s_mov_b32 m0, s36
	s_nop 0
	global_load_lds_dwordx4 v[210:211], off
	s_barrier
	s_waitcnt lgkmcnt(0)
	v_mfma_f32_16x16x32_bf16 v[60:63], v[128:131], v[144:147], v[60:63]
	v_mfma_f32_16x16x32_bf16 v[56:59], v[136:139], v[144:147], v[56:59]
	v_mfma_f32_16x16x32_bf16 v[52:55], v[128:131], v[152:155], v[52:55]
	v_mfma_f32_16x16x32_bf16 v[48:51], v[136:139], v[152:155], v[48:51]
	v_mfma_f32_16x16x32_bf16 v[36:39], v[128:131], v[160:163], v[36:39]
	v_mfma_f32_16x16x32_bf16 v[32:35], v[136:139], v[160:163], v[32:35]
	v_mfma_f32_16x16x32_bf16 v[20:23], v[128:131], v[168:171], v[20:23]
	v_mfma_f32_16x16x32_bf16 v[16:19], v[136:139], v[168:171], v[16:19]
	v_mfma_f32_16x16x32_bf16 v[60:63], v[132:135], v[148:151], v[60:63]
	s_add_i32 s31, s74, s87
	v_mfma_f32_16x16x32_bf16 v[56:59], v[140:143], v[148:151], v[56:59]
	v_lshl_add_u64 v[128:129], v[218:219], 0, s[60:61]
	v_mfma_f32_16x16x32_bf16 v[52:55], v[132:135], v[156:159], v[52:55]
	s_mov_b32 m0, s31
	v_mfma_f32_16x16x32_bf16 v[48:51], v[140:143], v[156:159], v[48:51]
	v_mfma_f32_16x16x32_bf16 v[36:39], v[132:135], v[164:167], v[36:39]
	v_mfma_f32_16x16x32_bf16 v[32:35], v[140:143], v[164:167], v[32:35]
	v_mfma_f32_16x16x32_bf16 v[20:23], v[132:135], v[172:175], v[20:23]
	v_mfma_f32_16x16x32_bf16 v[16:19], v[140:143], v[172:175], v[16:19]
	s_barrier
	s_nop 0
	global_load_lds_dwordx4 v[128:129], off
	v_lshl_add_u64 v[128:129], v[220:221], 0, s[60:61]
	s_add_i32 m0, s31, 0x2000
	s_nop 0
	global_load_lds_dwordx4 v[128:129], off
	s_waitcnt vmcnt(6)
	s_barrier
	v_mfma_f32_16x16x32_bf16 v[44:47], v[176:179], v[144:147], v[44:47]
	v_mfma_f32_16x16x32_bf16 v[40:43], v[184:187], v[144:147], v[40:43]
	v_mfma_f32_16x16x32_bf16 v[28:31], v[176:179], v[152:155], v[28:31]
	v_mfma_f32_16x16x32_bf16 v[24:27], v[184:187], v[152:155], v[24:27]
	v_mfma_f32_16x16x32_bf16 v[12:15], v[176:179], v[160:163], v[12:15]
	v_mfma_f32_16x16x32_bf16 v[8:11], v[184:187], v[160:163], v[8:11]
	v_mfma_f32_16x16x32_bf16 v[4:7], v[176:179], v[168:171], v[4:7]
	v_mfma_f32_16x16x32_bf16 v[0:3], v[184:187], v[168:171], v[0:3]
	v_mfma_f32_16x16x32_bf16 v[44:47], v[180:183], v[148:151], v[44:47]
	s_add_u32 s72, s72, 0x100
	v_mfma_f32_16x16x32_bf16 v[40:43], v[188:191], v[148:151], v[40:43]
	s_addc_u32 s73, s73, 0
	v_mfma_f32_16x16x32_bf16 v[28:31], v[180:183], v[156:159], v[28:31]
	s_add_u32 s78, s78, 0x100
	v_mfma_f32_16x16x32_bf16 v[24:27], v[188:191], v[156:159], v[24:27]
	s_addc_u32 s79, s79, 0
	v_mfma_f32_16x16x32_bf16 v[12:15], v[180:183], v[164:167], v[12:15]
	s_cmp_ge_u32 vcc_lo, s30
	v_mfma_f32_16x16x32_bf16 v[8:11], v[188:191], v[164:167], v[8:11]
	s_mov_b32 s74, vcc_lo
	v_mfma_f32_16x16x32_bf16 v[4:7], v[180:183], v[172:175], v[4:7]
	v_mfma_f32_16x16x32_bf16 v[0:3], v[188:191], v[172:175], v[0:3]
	s_barrier
	s_cbranch_scc0 .LBB0_522
	s_cmp_lt_i32 s91, 0
	s_mov_b64 s[72:73], -1
	s_cbranch_scc0 .LBB0_716
	s_lshl_b32 s78, s46, 8
	s_cmp_lt_i32 s81, 2
	s_cbranch_scc1 .LBB0_582
	s_cmp_lt_i32 s81, 3
	s_cbranch_scc1 .LBB0_579
	s_cmp_lg_u32 s81, 3
	s_cbranch_scc0 .LBB0_544
	v_lshl_or_b32 v128, s19, 7, v238
	v_ashrrev_i32_e32 v129, 31, v128
	v_lshl_add_u64 v[144:145], v[128:129], 1, s[24:25]
	v_and_b32_e32 v129, 64, v231
	v_xor_b32_e32 v128, 16, v231
	v_add_u32_e32 v129, 64, v129
	v_cmp_lt_i32_e32 vcc, v128, v129
	v_add_u32_e32 v146, s78, v202
	v_ashrrev_i32_e32 v147, 31, v146
	v_cndmask_b32_e32 v128, v231, v128, vcc
	v_lshlrev_b32_e32 v167, 2, v128
	v_xor_b32_e32 v128, 32, v231
	v_cmp_lt_i32_e32 vcc, v128, v129
	v_or_b32_e32 v156, 16, v146
	v_ashrrev_i32_e32 v157, 31, v156
	v_cndmask_b32_e32 v128, v231, v128, vcc
	v_lshlrev_b32_e32 v166, 2, v128
	v_lshlrev_b64 v[128:129], 12, v[146:147]
	v_lshl_add_u64 v[160:161], v[144:145], 0, v[128:129]
	global_load_dwordx4 v[140:143], v[160:161], off
	v_or_b32_e32 v152, 32, v146
	v_lshlrev_b64 v[128:129], 12, v[156:157]
	v_ashrrev_i32_e32 v153, 31, v152
	v_or_b32_e32 v148, 48, v146
	v_lshl_add_u64 v[158:159], v[144:145], 0, v[128:129]
	v_lshlrev_b64 v[128:129], 12, v[152:153]
	v_ashrrev_i32_e32 v149, 31, v148
	v_lshl_add_u64 v[154:155], v[144:145], 0, v[128:129]
	v_lshlrev_b64 v[128:129], 12, v[148:149]
	v_lshl_add_u64 v[150:151], v[144:145], 0, v[128:129]
	global_load_dwordx4 v[136:139], v[158:159], off
	global_load_dwordx4 v[132:135], v[154:155], off
	global_load_dwordx4 v[128:131], v[150:151], off
	v_mul_f32_e32 v163, 0xbfb8aa3b, v104
	v_exp_f32_e32 v163, v163
	v_mul_f32_e32 v162, 0xbfb8aa3b, v108
	v_exp_f32_e32 v162, v162
	v_add_f32_e32 v163, 1.0, v163
	v_rcp_f32_e32 v164, v163
	v_mul_f32_e32 v163, 0xbfb8aa3b, v109
	v_exp_f32_e32 v163, v163
	v_add_f32_e32 v162, 1.0, v162
	v_rcp_f32_e32 v162, v162
	v_add_f32_e32 v163, 1.0, v163
	v_rcp_f32_e32 v163, v163
	s_waitcnt vmcnt(0)
	v_lshlrev_b32_e32 v168, 16, v140
	v_and_b32_e32 v169, 0xffff0000, v140
	v_mul_f32_e32 v140, 0xbfb8aa3b, v105
	v_exp_f32_e32 v140, v140
	v_pk_fma_f32 v[162:163], v[162:163], v[124:125], v[168:169]
	v_lshlrev_b32_e32 v168, 16, v142
	v_and_b32_e32 v169, 0xffff0000, v142
	v_add_f32_e32 v140, 1.0, v140
	v_rcp_f32_e32 v165, v140
	v_mul_f32_e32 v140, 0xbfb8aa3b, v110
	v_exp_f32_e32 v140, v140
	v_mul_f32_e32 v142, 0xbfb8aa3b, v111
	v_pk_fma_f32 v[164:165], v[164:165], v[120:121], v[168:169]
	v_lshlrev_b32_e32 v170, 16, v141
	v_add_f32_e32 v140, 1.0, v140
	v_rcp_f32_e32 v168, v140
	v_mul_f32_e32 v140, 0xbfb8aa3b, v106
	v_and_b32_e32 v171, 0xffff0000, v141
	v_mul_f32_e32 v141, 0xbfb8aa3b, v107
	v_exp_f32_e32 v140, v140
	v_exp_f32_e32 v142, v142
	v_exp_f32_e32 v141, v141
	v_add_f32_e32 v140, 1.0, v140
	v_add_f32_e32 v142, 1.0, v142
	v_add_f32_e32 v141, 1.0, v141
	v_rcp_f32_e32 v140, v140
	v_rcp_f32_e32 v169, v142
	v_rcp_f32_e32 v141, v141
	v_lshlrev_b32_e32 v142, 16, v143
	v_and_b32_e32 v143, 0xffff0000, v143
	v_pk_fma_f32 v[168:169], v[168:169], v[126:127], v[170:171]
	v_pk_fma_f32 v[170:171], v[140:141], v[122:123], v[142:143]
	v_cvt_pk_bf16_f32 v140, v162, v163
	v_cvt_pk_bf16_f32 v141, v168, v169
	v_cvt_pk_bf16_f32 v142, v164, v165
	v_cvt_pk_bf16_f32 v143, v170, v171
	global_store_dwordx4 v[160:161], v[140:143], off
	v_pk_mul_f32 v[160:161], v[164:165], v[164:165]
	s_nop 0
	v_pk_mul_f32 v[140:141], v[162:163], v[162:163]
	v_pk_mul_f32 v[142:143], v[168:169], v[168:169]
	v_add_f32_e32 v140, v140, v141
	v_add_f32_e32 v142, v142, v143
	v_pk_mul_f32 v[162:163], v[170:171], v[170:171]
	v_add_f32_e32 v140, v140, v142
	v_add_f32_e32 v141, v160, v161
	v_add_f32_e32 v162, v162, v163
	v_add_f32_e32 v140, v141, v140
	v_add_f32_e32 v140, v162, v140
	v_mov_b32_e32 v141, v140
	s_nop 1
	v_permlane16_swap_b32_e32 v141, v140
	s_waitcnt lgkmcnt(0)
	v_add_f32_e32 v140, v140, v141
	v_mov_b32_e32 v141, v140
	s_nop 1
	v_permlane32_swap_b32_e32 v141, v140
	s_and_saveexec_b64 s[72:73], s[6:7]
	s_cbranch_execz .LBB0_529
	s_waitcnt lgkmcnt(0)
	v_add_f32_e32 v142, v140, v141
	s_lshl_b32 s74, s19, 2
	v_lshlrev_b64 v[140:141], 8, v[146:147]
	s_ashr_i32 s75, s74, 31
	v_lshl_add_u64 v[140:141], s[26:27], 0, v[140:141]
	v_lshl_add_u64 v[140:141], s[74:75], 2, v[140:141]
	s_lshl_b32 s50, s37, 2
	v_lshl_add_u64 v[140:141], v[140:141], 0, s[50:51]
	global_store_dword v[140:141], v142, off
